# NSA selected/window loops: barrier rotation (one wave group per SIMD takes its per-step barrier between softmax and PV, the other after PV before the ring store) so MFMA and VALU phases of the two wav
# speedup vs baseline: 1.0057x; 1.0003x over previous
; template <int NDVB, bool HAS_NEXT> DI void softmax_def(f32x16& sa0, f32x16& sa1, f32x16& sb0, f32x16& sb1, f32x16 (&O)[NDVB], float& muse, float& l, bool first, bf16x8 (&P)[4], bool check = true) {
;     ...
;   float sum = 0.f;
; #pragma unroll
;   for (int i = 0; i < 16; ++i) { sa0[i] = __builtin_amdgcn_exp2f(sa0[i]); sum += sa0[i]; }
; #pragma unroll
;   for (int i = 0; i < 16; ++i) { sa1[i] = __builtin_amdgcn_exp2f(sa1[i]); sum += sa1[i]; }
;   l += sum;
.LBB0_936:
	v_add_f32_e32 v112, 0, v112
	v_add_f32_e32 v112, v113, v112
	v_add_f32_e32 v112, v114, v112
	v_add_f32_e32 v112, v115, v112
	v_add_f32_e32 v112, v116, v112
	v_add_f32_e32 v112, v117, v112
	v_add_f32_e32 v112, v118, v112
	v_add_f32_e32 v112, v119, v112
	v_add_f32_e32 v112, v120, v112
	v_add_f32_e32 v112, v121, v112
	v_add_f32_e32 v112, v122, v112
	v_add_f32_e32 v112, v123, v112
	v_add_f32_e32 v112, v124, v112
	v_add_f32_e32 v112, v125, v112
	v_add_f32_e32 v112, v126, v112
	v_add_f32_e32 v112, v127, v112
	v_add_f32_e32 v96, v96, v112
	v_add_f32_e32 v96, v97, v96
	v_add_f32_e32 v96, v98, v96
	v_add_f32_e32 v96, v99, v96
	v_add_f32_e32 v96, v100, v96
	v_add_f32_e32 v96, v101, v96
	v_add_f32_e32 v96, v102, v96
	v_add_f32_e32 v96, v103, v96
	v_add_f32_e32 v96, v104, v96
	v_add_f32_e32 v96, v105, v96
	v_add_f32_e32 v96, v106, v96
	v_add_f32_e32 v96, v107, v96
	v_add_f32_e32 v96, v108, v96
	s_add_i32 s82, s6, 1
	v_add_f32_e32 v96, v109, v96
	s_cmp_lg_u32 s6, 2
	v_add_f32_e32 v96, v110, v96
	s_cselect_b32 s6, s82, 0
	s_add_i32 s89, s89, 2
	s_add_i32 s90, s90, 8
	v_add_f32_e32 v96, v111, v96
	s_cmp_ge_u32 s91, s88
	v_add_f32_e32 v219, v140, v96
	s_waitcnt lgkmcnt(0)
	s_mov_b64 s[82:83], 0
	s_cselect_b64 s[84:85], -1, 0

; DI unsigned cvtpk(float lo, float hi) { f32x2_t v = {lo, hi}; bf16x2_t b = __builtin_convertvector(v, bf16x2_t); return __builtin_bit_cast(unsigned, b); }
; #define MFMA32(a, b, c) __builtin_amdgcn_mfma_f32_32x32x16_bf16((a), (b), (c), 0, 0, 0)
; #define SBAR() __builtin_amdgcn_sched_barrier(0)
; template <int VSTR, int NDVB> DI void pv64(f32x16 (&O)[NDVB], const lds8* vp, const bf16x8 (&P)[4]) {
;   bf16x8 f[2][NDVB];
; #pragma unroll
;   for (int d = 0; d < NDVB; ++d) { const s16x4 lo = trrd(vp + d * 64), hi = trrd(vp + 8 * VSTR + d * 64); f[0][d] = __builtin_shufflevector(lo, hi, 0, 1, 2, 3, 4, 5, 6, 7); }
; #pragma unroll
;   for (int kk = 0; kk < 4; ++kk) {
;     if (kk < 3) {
; #pragma unroll
;       for (int d = 0; d < NDVB; ++d) { const s16x4 lo = trrd(vp + (16 * (kk + 1)) * VSTR + d * 64), hi = trrd(vp + (16 * (kk + 1) + 8) * VSTR + d * 64);
;         f[(kk + 1) & 1][d] = __builtin_shufflevector(lo, hi, 0, 1, 2, 3, 4, 5, 6, 7); }
;     }
;     SBAR();
;     __builtin_amdgcn_s_setprio(1);
; #pragma unroll
;     for (int d = 0; d < NDVB; ++d) O[d] = MFMA32(f[kk & 1][d], P[kk], O[d]);
;     __builtin_amdgcn_s_setprio(0);
;     SBAR();
;   }
; }
; template <int NDVB, bool HAS_NEXT> DI void softmax_def(f32x16& sa0, f32x16& sa1, f32x16& sb0, f32x16& sb1, f32x16 (&O)[NDVB], float& muse, float& l, bool first, bf16x8 (&P)[4], bool check = true) {
;     ...
;   float sum = 0.f;
; #pragma unroll
;   for (int i = 0; i < 16; ++i) { sa0[i] = __builtin_amdgcn_exp2f(sa0[i]); sum += sa0[i]; }
; #pragma unroll
;   for (int i = 0; i < 16; ++i) { sa1[i] = __builtin_amdgcn_exp2f(sa1[i]); sum += sa1[i]; }
;   l += sum;
;   u32x4 w;
;   w.x = cvtpk(sa0[0], sa0[1]); w.y = cvtpk(sa0[2], sa0[3]); w.z = cvtpk(sa0[4], sa0[5]); w.w = cvtpk(sa0[6], sa0[7]); P[0] = __builtin_bit_cast(bf16x8, w);
;   w.x = cvtpk(sa0[8], sa0[9]); w.y = cvtpk(sa0[10], sa0[11]); w.z = cvtpk(sa0[12], sa0[13]); w.w = cvtpk(sa0[14], sa0[15]); P[1] = __builtin_bit_cast(bf16x8, w);
;   w.x = cvtpk(sa1[0], sa1[1]); w.y = cvtpk(sa1[2], sa1[3]); w.z = cvtpk(sa1[4], sa1[5]); w.w = cvtpk(sa1[6], sa1[7]); P[2] = __builtin_bit_cast(bf16x8, w);
;   w.x = cvtpk(sa1[8], sa1[9]); w.y = cvtpk(sa1[10], sa1[11]); w.z = cvtpk(sa1[12], sa1[13]); w.w = cvtpk(sa1[14], sa1[15]); P[3] = __builtin_bit_cast(bf16x8, w);
.LBB0_951:
	v_exp_f32_e32 v108, v60
	v_add_u32_e32 v60, s95, v216
	v_exp_f32_e32 v96, v48
	v_exp_f32_e32 v97, v49
	v_exp_f32_e32 v98, v50
	v_exp_f32_e32 v99, v51
	v_exp_f32_e32 v100, v52
	v_exp_f32_e32 v101, v53
	v_exp_f32_e32 v102, v54
	v_exp_f32_e32 v103, v55
	v_exp_f32_e32 v104, v56
	v_exp_f32_e32 v105, v57
	v_exp_f32_e32 v106, v58
	v_exp_f32_e32 v107, v59
	v_exp_f32_e32 v124, v44
	v_exp_f32_e32 v125, v45
	v_exp_f32_e32 v126, v46
	v_exp_f32_e32 v127, v47
	ds_read_b64_tr_b16 v[44:45], v60 offset:9216
	ds_read_b64_tr_b16 v[46:47], v60 offset:10368
	ds_read_b64_tr_b16 v[50:51], v60 offset:10432
	ds_read_b64_tr_b16 v[48:49], v60 offset:9280
	ds_read_b64_tr_b16 v[52:53], v60 offset:11520
	ds_read_b64_tr_b16 v[54:55], v60 offset:12672
	ds_read_b64_tr_b16 v[58:59], v60 offset:12736
	ds_read_b64_tr_b16 v[56:57], v60 offset:11584
	v_exp_f32_e32 v109, v61
	v_exp_f32_e32 v110, v62
	v_exp_f32_e32 v111, v63
	v_exp_f32_e32 v112, v32
	v_exp_f32_e32 v113, v33
	v_exp_f32_e32 v114, v34
	v_exp_f32_e32 v115, v35
	v_exp_f32_e32 v116, v36
	v_exp_f32_e32 v117, v37
	v_exp_f32_e32 v118, v38
	v_exp_f32_e32 v119, v39
	v_exp_f32_e32 v120, v40
	v_exp_f32_e32 v121, v41
	v_exp_f32_e32 v122, v42
	v_exp_f32_e32 v123, v43
	v_cvt_pk_bf16_f32 v32, v96, v97
	v_cvt_pk_bf16_f32 v33, v98, v99
	v_cvt_pk_bf16_f32 v34, v100, v101
	v_cvt_pk_bf16_f32 v35, v102, v103
	v_cvt_pk_bf16_f32 v36, v104, v105
	v_cvt_pk_bf16_f32 v37, v106, v107
	v_cvt_pk_bf16_f32 v38, v108, v109
	v_cvt_pk_bf16_f32 v39, v110, v111
	v_cvt_pk_bf16_f32 v40, v112, v113
	v_cvt_pk_bf16_f32 v41, v114, v115
	v_cvt_pk_bf16_f32 v42, v116, v117
	v_cvt_pk_bf16_f32 v43, v118, v119
	v_cvt_pk_bf16_f32 v140, v120, v121
	v_cvt_pk_bf16_f32 v141, v122, v123
	v_cvt_pk_bf16_f32 v142, v124, v125
	v_cvt_pk_bf16_f32 v143, v126, v127
	v_readfirstlane_b32 vcc_lo, v200
	s_nop 1
	s_and_b32 vcc_lo, vcc_lo, 0x140
	s_bcnt1_i32_b32 vcc_lo, vcc_lo
	s_bitcmp1_b32 vcc_lo, 0
	s_cbranch_scc0 .Lns_ma
	s_barrier
.Lns_ma:
	s_setprio 1
	s_waitcnt lgkmcnt(6)
	v_mfma_f32_32x32x16_bf16 v[0:15], v[44:47], v[32:35], v[0:15]
	s_waitcnt lgkmcnt(4)
	v_mfma_f32_32x32x16_bf16 v[16:31], v[48:51], v[32:35], v[16:31]
	s_setprio 0
	ds_read_b64_tr_b16 v[32:33], v60 offset:13824
	ds_read_b64_tr_b16 v[34:35], v60 offset:14976
	ds_read_b64_tr_b16 v[46:47], v60 offset:15040
	ds_read_b64_tr_b16 v[44:45], v60 offset:13888
	s_setprio 1
	s_waitcnt lgkmcnt(6)
	v_mfma_f32_32x32x16_bf16 v[0:15], v[52:55], v[36:39], v[0:15]
	s_waitcnt lgkmcnt(4)
	v_mfma_f32_32x32x16_bf16 v[16:31], v[56:59], v[36:39], v[16:31]
	s_setprio 0
	ds_read_b64_tr_b16 v[48:49], v60 offset:16128
	ds_read_b64_tr_b16 v[50:51], v60 offset:17280
	ds_read_b64_tr_b16 v[146:147], v60 offset:17344
	ds_read_b64_tr_b16 v[144:145], v60 offset:16192
	s_setprio 1
	s_waitcnt lgkmcnt(6)
	v_mfma_f32_32x32x16_bf16 v[0:15], v[32:35], v[40:43], v[0:15]
	s_waitcnt lgkmcnt(4)
	v_mfma_f32_32x32x16_bf16 v[16:31], v[44:47], v[40:43], v[16:31]
	s_setprio 0
	s_setprio 1
	s_waitcnt lgkmcnt(2)
	v_mfma_f32_32x32x16_bf16 v[0:15], v[48:51], v[140:143], v[0:15]
	s_waitcnt lgkmcnt(0)
	v_mfma_f32_32x32x16_bf16 v[16:31], v[144:147], v[140:143], v[16:31]
	s_setprio 0
	v_readfirstlane_b32 vcc_lo, v200
	s_nop 1
	s_and_b32 vcc_lo, vcc_lo, 0x140
	s_bcnt1_i32_b32 vcc_lo, vcc_lo
	s_bitcmp1_b32 vcc_lo, 0
	s_cbranch_scc1 .Lns_ta
	s_barrier
.Lns_ta:
	s_andn2_b64 vcc, exec, s[82:83]
	s_cbranch_vccnz .LBB0_953
	s_addk_i32 s94, 0xb800
	s_cmp_lg_u32 s6, 0
	s_cselect_b32 s82, s94, 0x9000
	v_add_u32_e32 v32, s82, v215
	s_waitcnt vmcnt(1)
	ds_write_b128 v32, v[128:131]
	s_waitcnt vmcnt(0)
	ds_write_b128 v32, v[132:135] offset:9216
.LBB0_953:
	v_add_f32_e32 v32, 0, v96
	v_add_f32_e32 v32, v97, v32
	v_add_f32_e32 v32, v98, v32
	v_add_f32_e32 v32, v99, v32
	v_add_f32_e32 v32, v100, v32
	v_add_f32_e32 v32, v101, v32
	v_add_f32_e32 v32, v102, v32
	v_add_f32_e32 v32, v103, v32
	v_add_f32_e32 v32, v104, v32
	v_add_f32_e32 v32, v105, v32
	v_add_f32_e32 v32, v106, v32
	v_add_f32_e32 v32, v107, v32
	v_add_f32_e32 v32, v108, v32
	v_add_f32_e32 v32, v109, v32
	v_add_f32_e32 v32, v110, v32
	v_add_f32_e32 v32, v111, v32
	v_add_f32_e32 v32, v112, v32
	v_add_f32_e32 v32, v113, v32
	v_add_f32_e32 v32, v114, v32
	v_add_f32_e32 v32, v115, v32
	v_add_f32_e32 v32, v116, v32
	v_add_f32_e32 v32, v117, v32
	v_add_f32_e32 v32, v118, v32
	v_add_f32_e32 v32, v119, v32
	v_add_f32_e32 v32, v120, v32
	v_add_f32_e32 v32, v121, v32
	v_add_f32_e32 v32, v122, v32
	v_add_f32_e32 v32, v123, v32
	v_add_f32_e32 v32, v124, v32
	v_add_f32_e32 v32, v125, v32
	v_add_f32_e32 v32, v126, v32
	v_add_f32_e32 v32, v127, v32
	s_add_i32 s84, s89, -2
	v_add_f32_e32 v139, v219, v32
	s_mov_b64 s[82:83], -1
	s_cmp_ge_u32 s84, s88
	s_mov_b64 s[84:85], -1
	s_movk_i32 s95, 0x1ff
	s_waitcnt lgkmcnt(0)
	s_cbranch_scc1 .LBB0_937
	s_cmp_lt_u32 s89, s88
	s_cselect_b64 s[82:83], -1, 0
	s_cmp_ge_u32 s89, s88
	s_cbranch_scc1 .LBB0_956
	v_mov_b32_e32 v32, s90
	ds_read_b32 v32, v32 offset:12
	s_waitcnt lgkmcnt(0)
	v_readfirstlane_b32 s84, v32
	s_nop 1
	v_lshl_add_u32 v32, s84, 6, v212
	v_ashrrev_i32_e32 v33, 31, v32
	v_lshlrev_b64 v[32:33], 9, v[32:33]
	v_lshl_add_u64 v[34:35], v[194:195], 0, v[32:33]
	v_lshl_add_u64 v[32:33], v[196:197], 0, v[32:33]
	global_load_dwordx4 v[128:131], v[34:35], off
	global_load_dwordx4 v[132:135], v[32:33], off

; DI unsigned cvtpk(float lo, float hi) { f32x2_t v = {lo, hi}; bf16x2_t b = __builtin_convertvector(v, bf16x2_t); return __builtin_bit_cast(unsigned, b); }
; #define MFMA32(a, b, c) __builtin_amdgcn_mfma_f32_32x32x16_bf16((a), (b), (c), 0, 0, 0)
; #define SBAR() __builtin_amdgcn_sched_barrier(0)
; template <int VSTR, int NDVB> DI void pv64(f32x16 (&O)[NDVB], const lds8* vp, const bf16x8 (&P)[4]) {
;   bf16x8 f[2][NDVB];
; #pragma unroll
;   for (int d = 0; d < NDVB; ++d) { const s16x4 lo = trrd(vp + d * 64), hi = trrd(vp + 8 * VSTR + d * 64); f[0][d] = __builtin_shufflevector(lo, hi, 0, 1, 2, 3, 4, 5, 6, 7); }
; #pragma unroll
;   for (int kk = 0; kk < 4; ++kk) {
;     if (kk < 3) {
; #pragma unroll
;       for (int d = 0; d < NDVB; ++d) { const s16x4 lo = trrd(vp + (16 * (kk + 1)) * VSTR + d * 64), hi = trrd(vp + (16 * (kk + 1) + 8) * VSTR + d * 64);
;         f[(kk + 1) & 1][d] = __builtin_shufflevector(lo, hi, 0, 1, 2, 3, 4, 5, 6, 7); }
;     }
;     SBAR();
;     __builtin_amdgcn_s_setprio(1);
; #pragma unroll
;     for (int d = 0; d < NDVB; ++d) O[d] = MFMA32(f[kk & 1][d], P[kk], O[d]);
;     __builtin_amdgcn_s_setprio(0);
;     SBAR();
;   }
; }
; template <int NDVB, bool HAS_NEXT> DI void softmax_def(f32x16& sa0, f32x16& sa1, f32x16& sb0, f32x16& sb1, f32x16 (&O)[NDVB], float& muse, float& l, bool first, bf16x8 (&P)[4], bool check = true) {
;     ...
;   float sum = 0.f;
; #pragma unroll
;   for (int i = 0; i < 16; ++i) { sa0[i] = __builtin_amdgcn_exp2f(sa0[i]); sum += sa0[i]; }
; #pragma unroll
;   for (int i = 0; i < 16; ++i) { sa1[i] = __builtin_amdgcn_exp2f(sa1[i]); sum += sa1[i]; }
;   l += sum;
;   u32x4 w;
;   w.x = cvtpk(sa0[0], sa0[1]); w.y = cvtpk(sa0[2], sa0[3]); w.z = cvtpk(sa0[4], sa0[5]); w.w = cvtpk(sa0[6], sa0[7]); P[0] = __builtin_bit_cast(bf16x8, w);
;   w.x = cvtpk(sa0[8], sa0[9]); w.y = cvtpk(sa0[10], sa0[11]); w.z = cvtpk(sa0[12], sa0[13]); w.w = cvtpk(sa0[14], sa0[15]); P[1] = __builtin_bit_cast(bf16x8, w);
;   w.x = cvtpk(sa1[0], sa1[1]); w.y = cvtpk(sa1[2], sa1[3]); w.z = cvtpk(sa1[4], sa1[5]); w.w = cvtpk(sa1[6], sa1[7]); P[2] = __builtin_bit_cast(bf16x8, w);
;   w.x = cvtpk(sa1[8], sa1[9]); w.y = cvtpk(sa1[10], sa1[11]); w.z = cvtpk(sa1[12], sa1[13]); w.w = cvtpk(sa1[14], sa1[15]); P[3] = __builtin_bit_cast(bf16x8, w);
.LBB0_964:
	v_add_u32_e32 v141, s87, v216
	ds_read_b64_tr_b16 v[154:155], v141 offset:9216
	ds_read_b64_tr_b16 v[156:157], v141 offset:10368
	ds_read_b64_tr_b16 v[178:179], v141 offset:10432
	ds_read_b64_tr_b16 v[176:177], v141 offset:9280
	ds_read_b64_tr_b16 v[180:181], v141 offset:11520
	ds_read_b64_tr_b16 v[182:183], v141 offset:12672
	ds_read_b64_tr_b16 v[222:223], v141 offset:12736
	ds_read_b64_tr_b16 v[220:221], v141 offset:11584
	v_exp_f32_e32 v112, v112
	v_exp_f32_e32 v113, v113
	v_exp_f32_e32 v114, v114
	v_exp_f32_e32 v115, v115
	v_exp_f32_e32 v116, v116
	v_exp_f32_e32 v117, v117
	v_exp_f32_e32 v118, v118
	v_exp_f32_e32 v119, v119
	v_exp_f32_e32 v120, v120
	v_exp_f32_e32 v121, v121
	v_exp_f32_e32 v122, v122
	v_exp_f32_e32 v123, v123
	v_exp_f32_e32 v124, v124
	v_exp_f32_e32 v125, v125
	v_exp_f32_e32 v126, v126
	v_exp_f32_e32 v127, v127
	v_exp_f32_e32 v96, v96
	v_exp_f32_e32 v97, v97
	v_exp_f32_e32 v98, v98
	v_exp_f32_e32 v99, v99
	v_exp_f32_e32 v100, v100
	v_exp_f32_e32 v101, v101
	v_exp_f32_e32 v102, v102
	v_exp_f32_e32 v103, v103
	v_exp_f32_e32 v104, v104
	v_exp_f32_e32 v105, v105
	v_exp_f32_e32 v106, v106
	v_exp_f32_e32 v107, v107
	v_exp_f32_e32 v108, v108
	v_exp_f32_e32 v109, v109
	v_exp_f32_e32 v110, v110
	v_exp_f32_e32 v111, v111
	v_cvt_pk_bf16_f32 v142, v112, v113
	v_cvt_pk_bf16_f32 v143, v114, v115
	v_cvt_pk_bf16_f32 v144, v116, v117
	v_cvt_pk_bf16_f32 v145, v118, v119
	v_cvt_pk_bf16_f32 v146, v120, v121
	v_cvt_pk_bf16_f32 v147, v122, v123
	v_cvt_pk_bf16_f32 v148, v124, v125
	v_cvt_pk_bf16_f32 v149, v126, v127
	v_cvt_pk_bf16_f32 v150, v96, v97
	v_cvt_pk_bf16_f32 v151, v98, v99
	v_cvt_pk_bf16_f32 v152, v100, v101
	v_cvt_pk_bf16_f32 v153, v102, v103
	v_cvt_pk_bf16_f32 v224, v104, v105
	v_cvt_pk_bf16_f32 v225, v106, v107
	v_cvt_pk_bf16_f32 v226, v108, v109
	v_cvt_pk_bf16_f32 v227, v110, v111
	v_readfirstlane_b32 vcc_lo, v200
	s_nop 1
	s_and_b32 vcc_lo, vcc_lo, 0x140
	s_bcnt1_i32_b32 vcc_lo, vcc_lo
	s_bitcmp1_b32 vcc_lo, 0
	s_cbranch_scc0 .Lns_mb
	s_barrier
.Lns_mb:
	s_setprio 1
	s_waitcnt lgkmcnt(6)
	v_mfma_f32_32x32x16_bf16 v[0:15], v[154:157], v[142:145], v[0:15]
	s_waitcnt lgkmcnt(4)
	v_mfma_f32_32x32x16_bf16 v[16:31], v[176:179], v[142:145], v[16:31]
	s_setprio 0
	ds_read_b64_tr_b16 v[142:143], v141 offset:13824
	ds_read_b64_tr_b16 v[144:145], v141 offset:14976
	ds_read_b64_tr_b16 v[156:157], v141 offset:15040
	ds_read_b64_tr_b16 v[154:155], v141 offset:13888
	s_setprio 1
	s_waitcnt lgkmcnt(6)
	v_mfma_f32_32x32x16_bf16 v[0:15], v[180:183], v[146:149], v[0:15]
	s_waitcnt lgkmcnt(4)
	v_mfma_f32_32x32x16_bf16 v[16:31], v[220:223], v[146:149], v[16:31]
	s_setprio 0
	ds_read_b64_tr_b16 v[146:147], v141 offset:16128
	ds_read_b64_tr_b16 v[148:149], v141 offset:17280
	ds_read_b64_tr_b16 v[178:179], v141 offset:17344
	ds_read_b64_tr_b16 v[176:177], v141 offset:16192
	s_setprio 1
	s_waitcnt lgkmcnt(6)
	v_mfma_f32_32x32x16_bf16 v[0:15], v[142:145], v[150:153], v[0:15]
	s_waitcnt lgkmcnt(4)
	v_mfma_f32_32x32x16_bf16 v[16:31], v[154:157], v[150:153], v[16:31]
	s_setprio 0
	s_setprio 1
	s_waitcnt lgkmcnt(2)
	v_mfma_f32_32x32x16_bf16 v[0:15], v[146:149], v[224:227], v[0:15]
	s_waitcnt lgkmcnt(0)
	v_mfma_f32_32x32x16_bf16 v[16:31], v[176:179], v[224:227], v[16:31]
	s_setprio 0
	v_readfirstlane_b32 vcc_lo, v200
	s_nop 1
	s_and_b32 vcc_lo, vcc_lo, 0x140
	s_bcnt1_i32_b32 vcc_lo, vcc_lo
	s_bitcmp1_b32 vcc_lo, 0
	s_cbranch_scc1 .Lns_tb
	s_barrier
.Lns_tb:
	s_andn2_b64 vcc, exec, s[82:83]
	s_cbranch_vccnz .LBB0_936
	s_addk_i32 s86, 0xb800
	s_cmp_lg_u32 s6, 0
	s_cselect_b32 s82, s86, 0x9000
	v_add_u32_e32 v141, s82, v215
	s_waitcnt vmcnt(1)
	ds_write_b128 v141, v[128:131]
	s_waitcnt vmcnt(0)
	ds_write_b128 v141, v[132:135] offset:9216
	s_branch .LBB0_936

; template <int NDVB, bool HAS_NEXT> DI void softmax_def(f32x16& sa0, f32x16& sa1, f32x16& sb0, f32x16& sb1, f32x16 (&O)[NDVB], float& muse, float& l, bool first, bf16x8 (&P)[4], bool check = true) {
;     ...
;   float sum = 0.f;
; #pragma unroll
;   for (int i = 0; i < 16; ++i) { sa0[i] = __builtin_amdgcn_exp2f(sa0[i]); sum += sa0[i]; }
; #pragma unroll
;   for (int i = 0; i < 16; ++i) { sa1[i] = __builtin_amdgcn_exp2f(sa1[i]); sum += sa1[i]; }
;   l += sum;
.LBB0_979:
	v_add_f32_e32 v144, 0, v144
	v_add_f32_e32 v144, v145, v144
	v_add_f32_e32 v144, v146, v144
	v_add_f32_e32 v144, v147, v144
	v_add_f32_e32 v144, v148, v144
	v_add_f32_e32 v144, v149, v144
	v_add_f32_e32 v144, v150, v144
	v_add_f32_e32 v144, v151, v144
	v_add_f32_e32 v144, v152, v144
	v_add_f32_e32 v144, v153, v144
	v_add_f32_e32 v144, v154, v144
	v_add_f32_e32 v144, v155, v144
	v_add_f32_e32 v144, v156, v144
	v_add_f32_e32 v144, v157, v144
	v_add_f32_e32 v144, v158, v144
	v_add_f32_e32 v144, v159, v144
	v_add_f32_e32 v128, v128, v144
	v_add_f32_e32 v128, v129, v128
	v_add_f32_e32 v128, v130, v128
	v_add_f32_e32 v128, v131, v128
	v_add_f32_e32 v128, v132, v128
	v_add_f32_e32 v128, v133, v128
	v_add_f32_e32 v128, v134, v128
	v_add_f32_e32 v128, v135, v128
	v_add_f32_e32 v128, v136, v128
	v_add_f32_e32 v128, v137, v128
	v_add_f32_e32 v128, v138, v128
	v_add_f32_e32 v128, v139, v128
	v_add_f32_e32 v128, v140, v128
	s_add_i32 s8, s6, 1
	v_add_f32_e32 v128, v141, v128
	s_cmp_lg_u32 s6, 2
	v_add_f32_e32 v128, v142, v128
	s_cselect_b32 s6, s8, 0
	s_add_i32 s46, s46, 2
	s_add_i32 s0, s0, 8
	v_add_f32_e32 v128, v143, v128
	s_cmp_ge_u32 s47, s3
	v_add_f32_e32 v128, v223, v128
	s_waitcnt lgkmcnt(0)
	s_mov_b64 s[8:9], 0
	s_cselect_b64 s[10:11], -1, 0

; DI unsigned cvtpk(float lo, float hi) { f32x2_t v = {lo, hi}; bf16x2_t b = __builtin_convertvector(v, bf16x2_t); return __builtin_bit_cast(unsigned, b); }
; #define MFMA32(a, b, c) __builtin_amdgcn_mfma_f32_32x32x16_bf16((a), (b), (c), 0, 0, 0)
; #define SBAR() __builtin_amdgcn_sched_barrier(0)
; template <int VSTR, int NDVB> DI void pv64(f32x16 (&O)[NDVB], const lds8* vp, const bf16x8 (&P)[4]) {
;   bf16x8 f[2][NDVB];
; #pragma unroll
;   for (int d = 0; d < NDVB; ++d) { const s16x4 lo = trrd(vp + d * 64), hi = trrd(vp + 8 * VSTR + d * 64); f[0][d] = __builtin_shufflevector(lo, hi, 0, 1, 2, 3, 4, 5, 6, 7); }
; #pragma unroll
;   for (int kk = 0; kk < 4; ++kk) {
;     if (kk < 3) {
; #pragma unroll
;       for (int d = 0; d < NDVB; ++d) { const s16x4 lo = trrd(vp + (16 * (kk + 1)) * VSTR + d * 64), hi = trrd(vp + (16 * (kk + 1) + 8) * VSTR + d * 64);
;         f[(kk + 1) & 1][d] = __builtin_shufflevector(lo, hi, 0, 1, 2, 3, 4, 5, 6, 7); }
;     }
;     SBAR();
;     __builtin_amdgcn_s_setprio(1);
; #pragma unroll
;     for (int d = 0; d < NDVB; ++d) O[d] = MFMA32(f[kk & 1][d], P[kk], O[d]);
;     __builtin_amdgcn_s_setprio(0);
;     SBAR();
;   }
; }
; template <int NDVB, bool HAS_NEXT> DI void softmax_def(f32x16& sa0, f32x16& sa1, f32x16& sb0, f32x16& sb1, f32x16 (&O)[NDVB], float& muse, float& l, bool first, bf16x8 (&P)[4], bool check = true) {
;     ...
;   float sum = 0.f;
; #pragma unroll
;   for (int i = 0; i < 16; ++i) { sa0[i] = __builtin_amdgcn_exp2f(sa0[i]); sum += sa0[i]; }
; #pragma unroll
;   for (int i = 0; i < 16; ++i) { sa1[i] = __builtin_amdgcn_exp2f(sa1[i]); sum += sa1[i]; }
;   l += sum;
;   u32x4 w;
;   w.x = cvtpk(sa0[0], sa0[1]); w.y = cvtpk(sa0[2], sa0[3]); w.z = cvtpk(sa0[4], sa0[5]); w.w = cvtpk(sa0[6], sa0[7]); P[0] = __builtin_bit_cast(bf16x8, w);
;   w.x = cvtpk(sa0[8], sa0[9]); w.y = cvtpk(sa0[10], sa0[11]); w.z = cvtpk(sa0[12], sa0[13]); w.w = cvtpk(sa0[14], sa0[15]); P[1] = __builtin_bit_cast(bf16x8, w);
;   w.x = cvtpk(sa1[0], sa1[1]); w.y = cvtpk(sa1[2], sa1[3]); w.z = cvtpk(sa1[4], sa1[5]); w.w = cvtpk(sa1[6], sa1[7]); P[2] = __builtin_bit_cast(bf16x8, w);
;   w.x = cvtpk(sa1[8], sa1[9]); w.y = cvtpk(sa1[10], sa1[11]); w.z = cvtpk(sa1[12], sa1[13]); w.w = cvtpk(sa1[14], sa1[15]); P[3] = __builtin_bit_cast(bf16x8, w);
.LBB0_994:
	v_exp_f32_e32 v141, v124
	v_add_u32_e32 v124, s49, v216
	v_exp_f32_e32 v129, v112
	v_exp_f32_e32 v130, v113
	v_exp_f32_e32 v131, v114
	v_exp_f32_e32 v132, v115
	v_exp_f32_e32 v133, v116
	v_exp_f32_e32 v134, v117
	v_exp_f32_e32 v135, v118
	v_exp_f32_e32 v136, v119
	v_exp_f32_e32 v137, v120
	v_exp_f32_e32 v138, v121
	v_exp_f32_e32 v139, v122
	v_exp_f32_e32 v140, v123
	v_exp_f32_e32 v157, v108
	v_exp_f32_e32 v158, v109
	v_exp_f32_e32 v159, v110
	v_exp_f32_e32 v222, v111
	ds_read_b64_tr_b16 v[108:109], v124 offset:9216
	ds_read_b64_tr_b16 v[110:111], v124 offset:10368
	ds_read_b64_tr_b16 v[114:115], v124 offset:10432
	ds_read_b64_tr_b16 v[112:113], v124 offset:9280
	ds_read_b64_tr_b16 v[116:117], v124 offset:11520
	ds_read_b64_tr_b16 v[118:119], v124 offset:12672
	ds_read_b64_tr_b16 v[122:123], v124 offset:12736
	ds_read_b64_tr_b16 v[120:121], v124 offset:11584
	v_exp_f32_e32 v142, v125
	v_exp_f32_e32 v143, v126
	v_exp_f32_e32 v144, v127
	v_exp_f32_e32 v145, v96
	v_exp_f32_e32 v146, v97
	v_exp_f32_e32 v147, v98
	v_exp_f32_e32 v148, v99
	v_exp_f32_e32 v149, v100
	v_exp_f32_e32 v150, v101
	v_exp_f32_e32 v151, v102
	v_exp_f32_e32 v152, v103
	v_exp_f32_e32 v153, v104
	v_exp_f32_e32 v154, v105
	v_exp_f32_e32 v155, v106
	v_exp_f32_e32 v156, v107
	v_cvt_pk_bf16_f32 v96, v129, v130
	v_cvt_pk_bf16_f32 v97, v131, v132
	v_cvt_pk_bf16_f32 v98, v133, v134
	v_cvt_pk_bf16_f32 v99, v135, v136
	v_cvt_pk_bf16_f32 v100, v137, v138
	v_cvt_pk_bf16_f32 v101, v139, v140
	v_cvt_pk_bf16_f32 v102, v141, v142
	v_cvt_pk_bf16_f32 v103, v143, v144
	v_cvt_pk_bf16_f32 v104, v145, v146
	v_cvt_pk_bf16_f32 v105, v147, v148
	v_cvt_pk_bf16_f32 v106, v149, v150
	v_cvt_pk_bf16_f32 v107, v151, v152
	v_cvt_pk_bf16_f32 v224, v153, v154
	v_cvt_pk_bf16_f32 v225, v155, v156
	v_cvt_pk_bf16_f32 v226, v157, v158
	v_cvt_pk_bf16_f32 v227, v159, v222
	v_readfirstlane_b32 vcc_lo, v200
	s_nop 1
	s_and_b32 vcc_lo, vcc_lo, 0x140
	s_bcnt1_i32_b32 vcc_lo, vcc_lo
	s_bitcmp1_b32 vcc_lo, 0
	s_cbranch_scc0 .Lns_mc
	s_barrier
.Lns_mc:
	s_setprio 1
	s_waitcnt lgkmcnt(6)
	v_mfma_f32_32x32x16_bf16 v[32:47], v[108:111], v[96:99], v[32:47]
	s_waitcnt lgkmcnt(4)
	v_mfma_f32_32x32x16_bf16 v[48:63], v[112:115], v[96:99], v[48:63]
	s_setprio 0
	ds_read_b64_tr_b16 v[96:97], v124 offset:13824
	ds_read_b64_tr_b16 v[98:99], v124 offset:14976
	ds_read_b64_tr_b16 v[110:111], v124 offset:15040
	ds_read_b64_tr_b16 v[108:109], v124 offset:13888
	s_setprio 1
	s_waitcnt lgkmcnt(6)
	v_mfma_f32_32x32x16_bf16 v[32:47], v[116:119], v[100:103], v[32:47]
	s_waitcnt lgkmcnt(4)
	v_mfma_f32_32x32x16_bf16 v[48:63], v[120:123], v[100:103], v[48:63]
	s_setprio 0
	ds_read_b64_tr_b16 v[112:113], v124 offset:16128
	ds_read_b64_tr_b16 v[114:115], v124 offset:17280
	ds_read_b64_tr_b16 v[230:231], v124 offset:17344
	ds_read_b64_tr_b16 v[228:229], v124 offset:16192
	s_setprio 1
	s_waitcnt lgkmcnt(6)
	v_mfma_f32_32x32x16_bf16 v[32:47], v[96:99], v[104:107], v[32:47]
	s_waitcnt lgkmcnt(4)
	v_mfma_f32_32x32x16_bf16 v[48:63], v[108:111], v[104:107], v[48:63]
	s_setprio 0
	s_setprio 1
	s_waitcnt lgkmcnt(2)
	v_mfma_f32_32x32x16_bf16 v[32:47], v[112:115], v[224:227], v[32:47]
	s_waitcnt lgkmcnt(0)
	v_mfma_f32_32x32x16_bf16 v[48:63], v[228:231], v[224:227], v[48:63]
	s_setprio 0
	v_readfirstlane_b32 vcc_lo, v200
	s_nop 1
	s_and_b32 vcc_lo, vcc_lo, 0x140
	s_bcnt1_i32_b32 vcc_lo, vcc_lo
	s_bitcmp1_b32 vcc_lo, 0
	s_cbranch_scc1 .Lns_tc
	s_barrier
.Lns_tc:
	s_andn2_b64 vcc, exec, s[42:43]
	s_cbranch_vccnz .LBB0_996
	s_addk_i32 s48, 0xb800
	s_cmp_lg_u32 s6, 0
	s_cselect_b32 s8, s48, 0x9000
	v_add_u32_e32 v96, s8, v215
	s_waitcnt vmcnt(1)
	ds_write_b128 v96, v[176:179]
	s_waitcnt vmcnt(0)
	ds_write_b128 v96, v[180:183] offset:9216
.LBB0_996:
	v_add_f32_e32 v96, 0, v129
	v_add_f32_e32 v96, v130, v96
	v_add_f32_e32 v96, v131, v96
	v_add_f32_e32 v96, v132, v96
	v_add_f32_e32 v96, v133, v96
	v_add_f32_e32 v96, v134, v96
	v_add_f32_e32 v96, v135, v96
	v_add_f32_e32 v96, v136, v96
	v_add_f32_e32 v96, v137, v96
	v_add_f32_e32 v96, v138, v96
	v_add_f32_e32 v96, v139, v96
	v_add_f32_e32 v96, v140, v96
	v_add_f32_e32 v96, v141, v96
	v_add_f32_e32 v96, v142, v96
	v_add_f32_e32 v96, v143, v96
	v_add_f32_e32 v96, v144, v96
	v_add_f32_e32 v96, v145, v96
	v_add_f32_e32 v96, v146, v96
	v_add_f32_e32 v96, v147, v96
	v_add_f32_e32 v96, v148, v96
	v_add_f32_e32 v96, v149, v96
	v_add_f32_e32 v96, v150, v96
	v_add_f32_e32 v96, v151, v96
	v_add_f32_e32 v96, v152, v96
	v_add_f32_e32 v96, v153, v96
	v_add_f32_e32 v96, v154, v96
	v_add_f32_e32 v96, v155, v96
	v_add_f32_e32 v96, v156, v96
	v_add_f32_e32 v96, v157, v96
	v_add_f32_e32 v96, v158, v96
	v_add_f32_e32 v96, v159, v96
	v_add_f32_e32 v96, v222, v96
	s_add_i32 s10, s46, -2
	v_add_f32_e32 v222, v128, v96
	s_mov_b64 s[8:9], -1
	s_cmp_ge_u32 s10, s3
	s_mov_b64 s[10:11], -1
	s_waitcnt lgkmcnt(0)
	s_cbranch_scc1 .LBB0_980
	s_cmp_lt_u32 s46, s3
	s_cselect_b64 s[42:43], -1, 0
	s_cmp_ge_u32 s46, s3
	s_cbranch_scc1 .LBB0_999
	v_mov_b32_e32 v96, s0
	ds_read_b32 v96, v96 offset:12
	s_waitcnt lgkmcnt(0)
	v_readfirstlane_b32 s8, v96
	s_nop 1
	v_lshl_add_u32 v96, s8, 6, v212
	v_ashrrev_i32_e32 v97, 31, v96
	v_lshlrev_b64 v[96:97], 9, v[96:97]
	v_lshl_add_u64 v[98:99], v[194:195], 0, v[96:97]
	v_lshl_add_u64 v[96:97], v[196:197], 0, v[96:97]
	global_load_dwordx4 v[176:179], v[98:99], off offset:256
	global_load_dwordx4 v[180:183], v[96:97], off offset:256

; DI unsigned cvtpk(float lo, float hi) { f32x2_t v = {lo, hi}; bf16x2_t b = __builtin_convertvector(v, bf16x2_t); return __builtin_bit_cast(unsigned, b); }
; #define MFMA32(a, b, c) __builtin_amdgcn_mfma_f32_32x32x16_bf16((a), (b), (c), 0, 0, 0)
; #define SBAR() __builtin_amdgcn_sched_barrier(0)
; template <int VSTR, int NDVB> DI void pv64(f32x16 (&O)[NDVB], const lds8* vp, const bf16x8 (&P)[4]) {
;   bf16x8 f[2][NDVB];
; #pragma unroll
;   for (int d = 0; d < NDVB; ++d) { const s16x4 lo = trrd(vp + d * 64), hi = trrd(vp + 8 * VSTR + d * 64); f[0][d] = __builtin_shufflevector(lo, hi, 0, 1, 2, 3, 4, 5, 6, 7); }
; #pragma unroll
;   for (int kk = 0; kk < 4; ++kk) {
;     if (kk < 3) {
; #pragma unroll
;       for (int d = 0; d < NDVB; ++d) { const s16x4 lo = trrd(vp + (16 * (kk + 1)) * VSTR + d * 64), hi = trrd(vp + (16 * (kk + 1) + 8) * VSTR + d * 64);
;         f[(kk + 1) & 1][d] = __builtin_shufflevector(lo, hi, 0, 1, 2, 3, 4, 5, 6, 7); }
;     }
;     SBAR();
;     __builtin_amdgcn_s_setprio(1);
; #pragma unroll
;     for (int d = 0; d < NDVB; ++d) O[d] = MFMA32(f[kk & 1][d], P[kk], O[d]);
;     __builtin_amdgcn_s_setprio(0);
;     SBAR();
;   }
; }
; template <int NDVB, bool HAS_NEXT> DI void softmax_def(f32x16& sa0, f32x16& sa1, f32x16& sb0, f32x16& sb1, f32x16 (&O)[NDVB], float& muse, float& l, bool first, bf16x8 (&P)[4], bool check = true) {
;     ...
;   float sum = 0.f;
; #pragma unroll
;   for (int i = 0; i < 16; ++i) { sa0[i] = __builtin_amdgcn_exp2f(sa0[i]); sum += sa0[i]; }
; #pragma unroll
;   for (int i = 0; i < 16; ++i) { sa1[i] = __builtin_amdgcn_exp2f(sa1[i]); sum += sa1[i]; }
;   l += sum;
;   u32x4 w;
;   w.x = cvtpk(sa0[0], sa0[1]); w.y = cvtpk(sa0[2], sa0[3]); w.z = cvtpk(sa0[4], sa0[5]); w.w = cvtpk(sa0[6], sa0[7]); P[0] = __builtin_bit_cast(bf16x8, w);
;   w.x = cvtpk(sa0[8], sa0[9]); w.y = cvtpk(sa0[10], sa0[11]); w.z = cvtpk(sa0[12], sa0[13]); w.w = cvtpk(sa0[14], sa0[15]); P[1] = __builtin_bit_cast(bf16x8, w);
;   w.x = cvtpk(sa1[0], sa1[1]); w.y = cvtpk(sa1[2], sa1[3]); w.z = cvtpk(sa1[4], sa1[5]); w.w = cvtpk(sa1[6], sa1[7]); P[2] = __builtin_bit_cast(bf16x8, w);
;   w.x = cvtpk(sa1[8], sa1[9]); w.y = cvtpk(sa1[10], sa1[11]); w.z = cvtpk(sa1[12], sa1[13]); w.w = cvtpk(sa1[14], sa1[15]); P[3] = __builtin_bit_cast(bf16x8, w);
.LBB0_1007:
	v_add_u32_e32 v206, s49, v216
	ds_read_b64_tr_b16 v[236:237], v206 offset:9216
	ds_read_b64_tr_b16 v[238:239], v206 offset:10368
	ds_read_b64_tr_b16 v[242:243], v206 offset:10432
	ds_read_b64_tr_b16 v[240:241], v206 offset:9280
	ds_read_b64_tr_b16 v[244:245], v206 offset:11520
	ds_read_b64_tr_b16 v[246:247], v206 offset:12672
	ds_read_b64_tr_b16 v[250:251], v206 offset:12736
	ds_read_b64_tr_b16 v[248:249], v206 offset:11584
	v_exp_f32_e32 v144, v144
	v_exp_f32_e32 v145, v145
	v_exp_f32_e32 v146, v146
	v_exp_f32_e32 v147, v147
	v_exp_f32_e32 v148, v148
	v_exp_f32_e32 v149, v149
	v_exp_f32_e32 v150, v150
	v_exp_f32_e32 v151, v151
	v_exp_f32_e32 v152, v152
	v_exp_f32_e32 v153, v153
	v_exp_f32_e32 v154, v154
	v_exp_f32_e32 v155, v155
	v_exp_f32_e32 v156, v156
	v_exp_f32_e32 v157, v157
	v_exp_f32_e32 v158, v158
	v_exp_f32_e32 v159, v159
	v_exp_f32_e32 v128, v128
	v_exp_f32_e32 v129, v129
	v_exp_f32_e32 v130, v130
	v_exp_f32_e32 v131, v131
	v_exp_f32_e32 v132, v132
	v_exp_f32_e32 v133, v133
	v_exp_f32_e32 v134, v134
	v_exp_f32_e32 v135, v135
	v_exp_f32_e32 v136, v136
	v_exp_f32_e32 v137, v137
	v_exp_f32_e32 v138, v138
	v_exp_f32_e32 v139, v139
	v_exp_f32_e32 v140, v140
	v_exp_f32_e32 v141, v141
	v_exp_f32_e32 v142, v142
	v_exp_f32_e32 v143, v143
	v_cvt_pk_bf16_f32 v224, v144, v145
	v_cvt_pk_bf16_f32 v225, v146, v147
	v_cvt_pk_bf16_f32 v226, v148, v149
	v_cvt_pk_bf16_f32 v227, v150, v151
	v_cvt_pk_bf16_f32 v228, v152, v153
	v_cvt_pk_bf16_f32 v229, v154, v155
	v_cvt_pk_bf16_f32 v230, v156, v157
	v_cvt_pk_bf16_f32 v231, v158, v159
	v_cvt_pk_bf16_f32 v232, v128, v129
	v_cvt_pk_bf16_f32 v233, v130, v131
	v_cvt_pk_bf16_f32 v234, v132, v133
	v_cvt_pk_bf16_f32 v235, v134, v135
	v_cvt_pk_bf16_f32 v188, v136, v137
	v_cvt_pk_bf16_f32 v189, v138, v139
	v_cvt_pk_bf16_f32 v190, v140, v141
	v_cvt_pk_bf16_f32 v191, v142, v143
	v_readfirstlane_b32 vcc_lo, v200
	s_nop 1
	s_and_b32 vcc_lo, vcc_lo, 0x140
	s_bcnt1_i32_b32 vcc_lo, vcc_lo
	s_bitcmp1_b32 vcc_lo, 0
	s_cbranch_scc0 .Lns_md
	s_barrier
.Lns_md:
	s_setprio 1
	s_waitcnt lgkmcnt(6)
	v_mfma_f32_32x32x16_bf16 v[32:47], v[236:239], v[224:227], v[32:47]
	s_waitcnt lgkmcnt(4)
	v_mfma_f32_32x32x16_bf16 v[48:63], v[240:243], v[224:227], v[48:63]
	s_setprio 0
	ds_read_b64_tr_b16 v[224:225], v206 offset:13824
	ds_read_b64_tr_b16 v[226:227], v206 offset:14976
	ds_read_b64_tr_b16 v[238:239], v206 offset:15040
	ds_read_b64_tr_b16 v[236:237], v206 offset:13888
	s_setprio 1
	s_waitcnt lgkmcnt(6)
	v_mfma_f32_32x32x16_bf16 v[32:47], v[244:247], v[228:231], v[32:47]
	s_waitcnt lgkmcnt(4)
	v_mfma_f32_32x32x16_bf16 v[48:63], v[248:251], v[228:231], v[48:63]
	s_setprio 0
	ds_read_b64_tr_b16 v[228:229], v206 offset:16128
	ds_read_b64_tr_b16 v[230:231], v206 offset:17280
	ds_read_b64_tr_b16 v[242:243], v206 offset:17344
	ds_read_b64_tr_b16 v[240:241], v206 offset:16192
	s_setprio 1
	s_waitcnt lgkmcnt(6)
	v_mfma_f32_32x32x16_bf16 v[32:47], v[224:227], v[232:235], v[32:47]
	s_waitcnt lgkmcnt(4)
	v_mfma_f32_32x32x16_bf16 v[48:63], v[236:239], v[232:235], v[48:63]
	s_setprio 0
	s_setprio 1
	s_waitcnt lgkmcnt(2)
	v_mfma_f32_32x32x16_bf16 v[32:47], v[228:231], v[188:191], v[32:47]
	s_waitcnt lgkmcnt(0)
	v_mfma_f32_32x32x16_bf16 v[48:63], v[240:243], v[188:191], v[48:63]
	s_setprio 0
	v_readfirstlane_b32 vcc_lo, v200
	s_nop 1
	s_and_b32 vcc_lo, vcc_lo, 0x140
	s_bcnt1_i32_b32 vcc_lo, vcc_lo
	s_bitcmp1_b32 vcc_lo, 0
	s_cbranch_scc1 .Lns_td
	s_barrier
.Lns_td:
	s_andn2_b64 vcc, exec, s[42:43]
	s_cbranch_vccnz .LBB0_979
	s_addk_i32 s48, 0xb800
	s_cmp_lg_u32 s6, 0
	s_cselect_b32 s8, s48, 0x9000
	v_add_u32_e32 v188, s8, v215
	s_waitcnt vmcnt(1)
	ds_write_b128 v188, v[176:179]
	s_waitcnt vmcnt(0)
	ds_write_b128 v188, v[180:183] offset:9216
	s_branch .LBB0_979
.LBB0_1009:
	s_waitcnt lgkmcnt(0)
	s_barrier
	s_andn2_b64 vcc, exec, s[8:9]
	s_cbranch_vccz .LBB0_1012
	s_cbranch_execz .LBB0_1013
	s_branch .LBB0_1014
